# ml_out K/V staging: thread mapping (tid>>2, tid&3) so a wave-level load touches 16 rows x 64 B instead of 64 rows x 16 B
# speedup vs baseline: 1.0124x; 1.0071x over previous
; __device__ __forceinline__ bf16_t f2bf(float f) { return (bf16_t)(pack2(f, 0.f) & 0xffffu); }
; __device__ __forceinline__ int sidx(int dir, int b, int h, int n) { return ((dir * 8 + b) * 4 + h) * 18 + n; }
; __device__ __forceinline__ void ml_conv8_load(const bf16_t* z, int zcol, int b, bool isctx, int L, int pos, uint4* u) {
; #pragma unroll
;   for (int j = 0; j < 4; ++j) {
;     const int pp = pos + j - 1;
;     const int pc = pp < 0 ? 0 : (pp >= L ? L - 1 : pp);
;     u[j] = *(const uint4*)(z + (size_t)ml_row_pos(b, isctx, pc) * ZS + zcol);
;   }
; __device__ void ml_out_tile(unsigned char* lds, const Params& p, int l, int b, int h, int n) {
;     ...
;   {
;     const int s = tid & 127, ec0 = tid >> 7;
;     const int row = ml_row_pos(b, isctx, p0 + s);
; #pragma unroll 2
;     for (int i = 0; i < 4; ++i) {
;       const int ec = ec0 + 4 * i;
;       float k8[8], v8[8];
;       ml_conv8(z, wc, 768 + 512 + h * 128 + ec * 8, 512 + h * 128 + ec * 8, b, isctx, L, p0 + s, k8);
; #pragma unroll
;       for (int e = 0; e < 8; ++e) k8[e] *= 0.08838834764831845f;
;       *(uint4*)(Ks + s * 136 + ec * 8) = pack8(k8);
;       const uint4 vu = *(const uint4*)(z + (size_t)row * ZS + 768 + 1024 + h * 128 + ec * 8);
;       unpack8(vu, v8);
; #pragma unroll
;       for (int e = 0; e < 8; ++e) VT[(ec * 8 + e) * 136 + s] = f2bf(v8[e]);
;     }
.LBB0_729:
	v_lshrrev_b32_e32 v2, 2, v197
	v_or_b32_e32 v3, s4, v2
	v_lshlrev_b32_e32 v0, 6, v2
	v_and_b32_e32 v0, 0x7c0, v0
	v_lshrrev_b32_e32 v1, 5, v3
	v_add3_u32 v0, v0, v1, v27
	v_add_u32_e32 v1, v26, v3
	v_cndmask_b32_e64 v0, v0, v1, s[38:39]
	s_and_b64 s[0:1], s[38:39], exec
	s_cselect_b32 s22, 0x100, s6
	s_lshl_b32 s96, s21, 7
	v_min_u32_e32 v1, s22, v3
	v_add_u32_e32 v5, 1, v3
	v_add_u32_e32 v1, -1, v1
	v_cmp_lt_i32_e32 vcc, 0, v3
	v_min_u32_e32 v5, s22, v5
	s_cmp_gt_i32 s4, -1
	v_add_u32_e32 v7, 2, v3
	v_cmp_ge_i32_e64 s[4:5], s22, v3
	v_cndmask_b32_e32 v1, 0, v1, vcc
	v_add_u32_e32 v5, -1, v5
	s_cselect_b64 s[0:1], -1, 0
	v_min_u32_e32 v6, s22, v7
	s_and_b64 s[4:5], vcc, s[4:5]
	v_cmp_gt_u32_e32 vcc, s22, v3
	v_cndmask_b32_e64 v5, 0, v5, s[0:1]
	v_add_u32_e32 v6, -1, v6
	v_cmp_lt_i32_e64 s[0:1], -2, v3
	v_add_u32_e32 v11, 3, v3
	v_cndmask_b32_e64 v8, 0, 1.0, vcc
	v_cmp_ge_i32_e32 vcc, s22, v7
	v_lshlrev_b32_e32 v7, 6, v1
	v_cndmask_b32_e64 v9, 0, v6, s[0:1]
	v_min_u32_e32 v6, s22, v11
	s_and_b64 s[0:1], s[0:1], vcc
	v_cmp_ge_i32_e32 vcc, s22, v11
	v_and_b32_e32 v7, 0x7c0, v7
	v_ashrrev_i32_e32 v11, 5, v1
	v_add3_u32 v7, v7, v11, v27
	v_lshlrev_b32_e32 v11, 6, v5
	v_and_b32_e32 v11, 0x7c0, v11
	v_ashrrev_i32_e32 v16, 5, v5
	v_add_u32_e32 v6, -1, v6
	v_cmp_lt_i32_e64 s[2:3], -3, v3
	v_add3_u32 v11, v11, v16, v27
	v_lshlrev_b32_e32 v16, 6, v9
	v_cndmask_b32_e64 v13, 0, v6, s[2:3]
	v_and_b32_e32 v16, 0x7c0, v16
	v_ashrrev_i32_e32 v17, 5, v9
	v_add_u32_e32 v1, v26, v1
	v_add3_u32 v20, v16, v17, v27
	v_lshlrev_b32_e32 v16, 6, v13
	v_cndmask_b32_e64 v10, 0, 1.0, s[0:1]
	s_and_b64 s[0:1], s[2:3], vcc
	v_mov_b64_e32 v[14:15], s[88:89]
	v_add_u32_e32 v5, v26, v5
	v_and_b32_e32 v16, 0x7c0, v16
	v_ashrrev_i32_e32 v17, 5, v13
	v_cndmask_b32_e64 v1, v7, v1, s[38:39]
	v_cndmask_b32_e64 v12, 0, 1.0, s[0:1]
	v_mad_i64_i32 v[14:15], s[0:1], v0, s92, v[14:15]
	v_add_u32_e32 v9, v26, v9
	v_add3_u32 v22, v16, v17, v27
	v_mad_i64_i32 v[16:17], s[2:3], v1, s92, 0
	v_cndmask_b32_e64 v1, v11, v5, s[38:39]
	v_ashrrev_i32_e32 v202, 4, v197
	s_lshl_b32 s0, s21, 8
	s_mov_b32 s1, s97
	v_add_u32_e32 v13, v26, v13
	v_mad_i64_i32 v[18:19], s[2:3], v1, s92, 0
	v_cndmask_b32_e64 v1, v20, v9, s[38:39]
	v_lshl_add_u64 v[14:15], v[14:15], 0, s[0:1]
	v_mad_i64_i32 v[20:21], s[2:3], v1, s92, 0
	v_cndmask_b32_e64 v1, v22, v13, s[38:39]
	v_and_b32_e32 v29, 3, v197
	s_movk_i32 s1, 0x880
	v_lshlrev_b32_e32 v4, 3, v29
	v_mad_i64_i32 v[22:23], s[2:3], v1, s92, 0
	v_mul_lo_u32 v1, v29, s1
	v_mov_b32_e32 v192, s0
	v_ashrrev_i32_e32 v5, 31, v4
	v_lshl_add_u32 v28, v2, 1, v1
	v_mad_i64_i32 v[0:1], s[0:1], v0, s92, v[192:193]
	v_lshl_add_u64 v[0:1], v[4:5], 1, v[0:1]
	v_cndmask_b32_e64 v6, 0, 1.0, s[4:5]
	v_mul_u32_u24_e32 v3, 0x110, v2
	v_lshl_add_u64 v[24:25], s[88:89], 0, v[0:1]
	v_lshlrev_b32_e32 v0, 4, v29
	s_mov_b32 s0, 0x8800
	v_readlane_b32 s14, v254, 19
	v_and_b32_e32 v241, 15, v197
	v_mov_b32_e32 v7, v6
	v_mov_b32_e32 v9, v8
	v_mov_b32_e32 v11, v10
	v_mov_b32_e32 v13, v12
	v_add3_u32 v29, v3, v0, s0
	s_mov_b64 s[0:1], 0
	s_movk_i32 s7, 0x1000
	s_movk_i32 s8, 0x2000
	s_movk_i32 s9, 0x3000
	s_mov_b64 s[2:3], 0x1800
	s_mov_b64 s[4:5], 0x2800
	s_mov_b64 s[10:11], 0x3800
	s_mov_b32 s6, 0x3db504f3
	v_readlane_b32 s15, v254, 20
